# pc1_pc2_tile_decode_shifts
# baseline (speedup 1.0000x reference)
;     __device__ bool next(int i, Unit& u) const {
;         const long L = (long)i * G + c; if (L >= nwg) return false;
;         int wgid = (int)L; { const int q = nwg / NXCD, r = nwg % NXCD, xcd = wgid % NXCD, off = wgid / NXCD; wgid = (xcd < r ? xcd * (q + 1) : r * (q + 1) + (xcd - r) * q) + off; }
;         const int nig = WGM * nN, gid = wgid / nig, fm = gid * WGM, gsz = (nM - fm) < WGM ? (nM - fm) : WGM;
;         u.pm = fm + ((wgid % nig) % gsz); u.pn = (wgid % nig) / gsz; return true;
;     }
.LBB0_488:
	s_add_i32 s45, s45, 1
	s_mul_i32 s0, s45, s49
	s_mul_hi_u32 s1, s45, s43
	s_add_i32 s1, s1, s0
	s_mul_i32 s0, s45, s43
	s_add_u32 s20, s0, s2
	s_addc_u32 s21, s1, s37
	v_cmp_gt_i64_e32 vcc, s[20:21], v[184:185]
	v_cmp_lt_i64_e64 s[0:1], s[20:21], v[182:183]
	s_cbranch_vccnz .LBB0_490
	s_and_b32 s16, s20, 7
	s_mul_i32 s16, s16, 0x60
	s_lshr_b32 s17, s20, 3
	s_add_i32 s17, s16, s17
	s_lshr_b32 s18, s17, 4
	s_lshl_b32 s18, s18, 2
	s_and_b32 s16, s17, 3
	s_add_i32 s18, s18, s16
	s_bfe_u32 s16, s17, 0x20002

;     __device__ bool next(int i, Unit& u) const {
;         const long L = (long)i * G + c; if (L >= nwg) return false;
;         int wgid = (int)L; { const int q = nwg / NXCD, r = nwg % NXCD, xcd = wgid % NXCD, off = wgid / NXCD; wgid = (xcd < r ? xcd * (q + 1) : r * (q + 1) + (xcd - r) * q) + off; }
;         const int nig = WGM * nN, gid = wgid / nig, fm = gid * WGM, gsz = (nM - fm) < WGM ? (nM - fm) : WGM;
;         u.pm = fm + ((wgid % nig) % gsz); u.pn = (wgid % nig) / gsz; return true;
;     }
.LBB0_561:
	s_add_i32 s52, s52, 1
	s_mul_i32 s0, s52, s43
	s_mul_hi_u32 s1, s52, s39
	s_add_i32 s1, s1, s0
	s_mul_i32 s0, s52, s39
	s_add_u32 s16, s0, s2
	s_addc_u32 s17, s1, s33
	v_cmp_gt_i64_e32 vcc, s[16:17], v[148:149]
	v_cmp_lt_i64_e64 s[0:1], s[16:17], v[146:147]
	s_cbranch_vccnz .LBB0_563
	s_and_b32 s12, s16, 7
	s_mul_i32 s12, s12, 0x60
	s_lshr_b32 s13, s16, 3
	s_add_i32 s13, s12, s13
	s_lshr_b32 s14, s13, 4
	s_lshl_b32 s14, s14, 2
	s_and_b32 s12, s13, 3
	s_add_i32 s14, s14, s12
	s_bfe_u32 s12, s13, 0x20002
